# prep conv stage: half 1's per-row decay/beta work runs on its wave 1 (another SIMD) instead of its wave 0, so no SIMD hosts two of the heavier waves
# baseline (speedup 1.0000x reference)
.Lps_j:
	v_mov_b32_e32 v0, s1
	s_mov_b64 s[0:1], -1
	s_cbranch_scc0 .LBB0_550
	v_lshl_add_u32 v0, v0, 1, v147
	v_sub_u32_e32 v3, 0, v0
	v_max_i32_e32 v3, v0, v3
	v_mul_hi_u32 v4, v3, v247
	v_mul_lo_u32 v5, v4, s17
	v_sub_u32_e32 v3, v3, v5
	v_add_u32_e32 v5, 1, v4
	v_cmp_le_u32_e32 vcc, s17, v3
	v_ashrrev_i32_e32 v2, 31, v0
	v_readlane_b32 s0, v254, 33
	v_cndmask_b32_e32 v4, v4, v5, vcc
	v_subrev_u32_e32 v5, s17, v3
	v_cndmask_b32_e32 v3, v3, v5, vcc
	v_add_u32_e32 v5, 1, v4
	v_cmp_le_u32_e32 vcc, s17, v3
	v_mov_b32_e32 v148, v156
	v_bfrev_b32_e32 v165, 1
	v_cndmask_b32_e32 v3, v4, v5, vcc
	v_xor_b32_e32 v3, v3, v2
	v_sub_u32_e32 v162, v3, v2
	v_mul_lo_u32 v2, v162, s17
	v_sub_u32_e32 v161, v0, v2
	v_and_b32_e32 v164, 1, v162
	v_add_u32_e32 v2, s0, v161
	v_ashrrev_i32_e32 v0, 4, v162
	v_sub_u32_e32 v3, s36, v2
	v_cmp_eq_u32_e64 s[44:45], 0, v164
	v_readlane_b32 s0, v254, 31
	v_readlane_b32 s1, v254, 32
	v_cndmask_b32_e64 v2, v3, v2, s[44:45]
	v_lshl_add_u32 v3, v0, 8, v246
	v_lshlrev_b32_e32 v0, 12, v0
	v_cndmask_b32_e64 v26, v0, v3, s[0:1]
	v_bfe_u32 v163, v162, 1, 3
	v_ashrrev_i32_e32 v27, 31, v26
	v_lshlrev_b32_e32 v4, 6, v2
	v_lshrrev_b32_e32 v130, 6, v148
	v_cmp_eq_u32_e64 s[46:47], v130, v147
	v_lshl_or_b32 v130, v164, 3, v163
	v_lshlrev_b32_e32 v130, 2, v130
	s_nop 0
	v_readfirstlane_b32 s100, v130
	s_nop 4
	s_load_dword s101, s[82:83], s100
	s_load_dword s100, s[80:81], s100
	v_mov_b32_e32 v130, 0
	v_mov_b32_e32 v166, 0
	s_and_saveexec_b64 s[0:1], s[46:47]
	s_cbranch_execz .LBB0_558
	v_and_b32_e32 v2, 63, v148
	v_xor_b32_e32 v0, 63, v2
	v_ashrrev_i32_e32 v5, 31, v4
	v_cndmask_b32_e64 v0, v0, v2, s[44:45]
	v_lshl_add_u64 v[2:3], v[4:5], 0, v[26:27]
	v_or_b32_e32 v2, v2, v0
	v_readlane_b32 s22, v251, 58
	v_lshlrev_b64 v[2:3], 7, v[2:3]
	v_readlane_b32 s23, v251, 59
	v_lshlrev_b32_e32 v0, 5, v164
	s_nop 0
	v_lshl_add_u64 v[2:3], s[22:23], 0, v[2:3]
	v_lshl_add_u64 v[2:3], v[2:3], 0, v[0:1]
	v_lshlrev_b32_e32 v0, 2, v163
	v_lshl_add_u64 v[2:3], v[2:3], 0, v[0:1]
	global_load_dword v165, v[2:3], off
	global_load_dword v166, v[2:3], off offset:64

.LBB0_597:
	s_or_b64 exec, exec, s[22:23]
	v_mov_b32_e32 v0, s100
	v_mul_f32_e32 v165, 0xbfb8aa3b, v165
	s_mov_b32 s2, 0x3fb8aa3b
	v_exp_f32_e32 v3, v165
	s_waitcnt vmcnt(0)
	v_mul_f32_e32 v4, 0x3fb8aa3b, v0
	v_fma_f32 v5, v0, s2, -v4
	v_rndne_f32_e32 v6, v4
	v_fmac_f32_e32 v5, 0x32a5705f, v0
	v_sub_f32_e32 v4, v4, v6
	v_add_f32_e32 v4, v4, v5
	v_exp_f32_e32 v4, v4
	v_cvt_i32_f32_e32 v5, v6
	s_mov_b32 s2, 0xc2ce8ed0
	v_cmp_ngt_f32_e32 vcc, s2, v0
	s_mov_b32 s2, 0x42b17218
	v_ldexp_f32 v4, v4, v5
	v_cndmask_b32_e32 v4, 0, v4, vcc
	v_cmp_nlt_f32_e32 vcc, s2, v0
	v_and_b32_e32 v5, 64, v238
	v_add_u32_e32 v6, -1, v238
	v_cndmask_b32_e32 v0, v239, v4, vcc
	v_cmp_lt_i32_e32 vcc, v6, v5
	v_mul_f32_e64 v4, v2, -v0
	v_add_f32_e32 v3, 1.0, v3
	v_cndmask_b32_e32 v6, v6, v238, vcc
	v_lshlrev_b32_e32 v6, 2, v6
	ds_bpermute_b32 v6, v6, v4
	v_cmp_eq_u32_e32 vcc, 0, v160
	v_rcp_f32_e32 v3, v3
	s_waitcnt lgkmcnt(0)
	v_fma_f32 v0, v2, -v0, v6
	v_add_u32_e32 v2, -2, v238
	v_cndmask_b32_e32 v0, v0, v4, vcc
	v_cmp_lt_i32_e32 vcc, v2, v5
	s_nop 1
	v_cndmask_b32_e32 v2, v2, v238, vcc
	v_lshlrev_b32_e32 v2, 2, v2
	ds_bpermute_b32 v2, v2, v0
	v_cmp_gt_u32_e32 vcc, 2, v160
	s_waitcnt lgkmcnt(0)
	v_add_f32_e32 v2, v0, v2
	v_cndmask_b32_e32 v0, v2, v0, vcc
	v_add_u32_e32 v2, -4, v238
	v_cmp_lt_i32_e32 vcc, v2, v5
	s_nop 1
	v_cndmask_b32_e32 v2, v2, v238, vcc
	v_lshlrev_b32_e32 v2, 2, v2
	ds_bpermute_b32 v2, v2, v0
	v_cmp_gt_u32_e32 vcc, 4, v160
	s_waitcnt lgkmcnt(0)
	v_add_f32_e32 v2, v0, v2
	v_cndmask_b32_e32 v0, v2, v0, vcc
	v_add_u32_e32 v2, -8, v238
	v_cmp_lt_i32_e32 vcc, v2, v5
	s_nop 1
	v_cndmask_b32_e32 v2, v2, v238, vcc
	v_lshlrev_b32_e32 v2, 2, v2
	ds_bpermute_b32 v2, v2, v0
	v_cmp_gt_u32_e32 vcc, 8, v160
	s_waitcnt lgkmcnt(0)
	v_add_f32_e32 v2, v0, v2
	v_cndmask_b32_e32 v0, v2, v0, vcc
	v_add_u32_e32 v2, -16, v238
	v_cmp_lt_i32_e32 vcc, v2, v5
	s_nop 1
	v_cndmask_b32_e32 v2, v2, v238, vcc
	v_lshlrev_b32_e32 v2, 2, v2
	ds_bpermute_b32 v2, v2, v0
	v_cmp_gt_u32_e32 vcc, 16, v160
	s_waitcnt lgkmcnt(0)
	v_add_f32_e32 v2, v0, v2
	v_cndmask_b32_e32 v0, v2, v0, vcc
	v_subrev_u32_e32 v2, 32, v238
	v_cmp_lt_i32_e32 vcc, v2, v5
	s_nop 1
	v_cndmask_b32_e32 v2, v2, v238, vcc
	v_lshlrev_b32_e32 v2, 2, v2
	ds_bpermute_b32 v2, v2, v0
	v_cmp_gt_u32_e32 vcc, 32, v160
	s_waitcnt lgkmcnt(0)
	v_add_f32_e32 v2, v0, v2
	v_cndmask_b32_e32 v0, v2, v0, vcc
	v_lshl_add_u32 v2, v160, 2, v157
	ds_write_b32 v2, v3
	v_lshl_add_u32 v2, v160, 2, v157
	ds_write_b32 v2, v0 offset:256
